# prep S3 rewrite (batched raw prefetch, pipelined solve) + 40-byte code placement shift
# speedup vs baseline: 1.0192x; 1.0021x over previous
.LBB0_6:
	s_load_dwordx16 s[36:51], s[0:1], 0x0
	s_load_dword s3, s[0:1], 0xe0
	s_mul_i32 s2, s19, s18
	v_lshrrev_b32_e32 v1, 20, v0
	v_lshrrev_b32_e32 v0, 10, v0
	s_waitcnt lgkmcnt(0)
	v_writelane_b32 v252, s36, 4
	s_mul_i32 s2, s2, s3
	v_or_b32_e32 v0, v0, v1
	v_writelane_b32 v252, s37, 5
	v_writelane_b32 v252, s38, 6
	v_writelane_b32 v252, s39, 7
	v_writelane_b32 v252, s40, 8
	v_writelane_b32 v252, s41, 9
	v_writelane_b32 v252, s42, 10
	v_writelane_b32 v252, s43, 11
	v_writelane_b32 v252, s44, 12
	v_writelane_b32 v252, s45, 13
	v_writelane_b32 v252, s46, 14
	v_writelane_b32 v252, s47, 15
	v_writelane_b32 v252, s48, 16
	v_writelane_b32 v252, s49, 17
	v_writelane_b32 v252, s50, 18
	v_writelane_b32 v252, s51, 19
	v_writelane_b32 v252, s2, 20
	s_add_u32 s2, s46, 0x2000
	s_addc_u32 s3, s47, 0
	v_writelane_b32 v252, s2, 21
	s_load_dwordx16 s[56:71], s[0:1], 0x80
	v_mbcnt_lo_u32_b32 v2, -1, 0
	v_writelane_b32 v252, s3, 22
	s_add_u32 s2, s46, 0x1000
	s_addc_u32 s3, s47, 0
	v_writelane_b32 v252, s2, 23
	s_cmp_gt_i32 s17, -1
	s_load_dwordx16 s[40:55], s[0:1], 0x40
	v_writelane_b32 v252, s3, 24
	s_cselect_b64 s[2:3], -1, 0
	v_writelane_b32 v252, s2, 25
	v_mov_b32_e32 v1, 0
	v_mov_b32_e32 v205, 0x260
	v_writelane_b32 v252, s3, 26
	s_add_u32 s2, s14, 0x200
	s_addc_u32 s3, s15, 0
	v_writelane_b32 v252, s2, 27
	v_mov_b32_e32 v218, 0x358637bd
	v_mov_b32_e32 v219, 1
	v_writelane_b32 v252, s3, 28
	s_add_u32 s2, s14, 0x1000
	s_addc_u32 s3, s15, 0
	v_writelane_b32 v252, s2, 29
	v_mbcnt_hi_u32_b32 v222, -1, v2
	v_not_b32_e32 v224, 63
	v_writelane_b32 v252, s3, 30
	s_add_u32 s2, s14, 0x1100
	s_addc_u32 s3, s15, 0
	v_writelane_b32 v252, s2, 31
	v_mov_b32_e32 v225, 0xffffff80
	v_mov_b32_e32 v232, 0x10d00
	v_writelane_b32 v252, s3, 32
	s_add_u32 s2, s14, 0x1200
	s_addc_u32 s3, s15, 0
	v_writelane_b32 v252, s2, 33
	v_mov_b32_e32 v223, 0x15100
	v_mov_b32_e32 v228, 0x110
	v_writelane_b32 v252, s3, 34
	s_add_u32 s2, s14, 0x1300
	s_addc_u32 s3, s15, 0
	v_writelane_b32 v252, s2, 35
	s_cmp_eq_u32 s6, 15
	v_mov_b32_e32 v229, 0x100
	v_writelane_b32 v252, s3, 36
	s_cselect_b64 s[2:3], -1, 0
	v_writelane_b32 v252, s2, 37
	s_cmp_eq_u32 s6, 14
	v_mov_b32_e32 v230, 0xf149f2ca
	v_writelane_b32 v252, s3, 38
	s_cselect_b64 s[2:3], -1, 0
	v_writelane_b32 v252, s2, 39
	s_cmp_eq_u32 s6, 13
	v_mov_b32_e32 v231, 0x4e6e6b28
	v_writelane_b32 v252, s3, 40
	s_cselect_b64 s[2:3], -1, 0
	v_writelane_b32 v252, s2, 41
	s_cmp_eq_u32 s6, 12
	v_mov_b64_e32 v[158:159], 0x200
	v_writelane_b32 v252, s3, 42
	s_cselect_b64 s[2:3], -1, 0
	v_writelane_b32 v252, s2, 43
	s_cmp_eq_u32 s6, 11
	v_mov_b64_e32 v[160:161], 0x1ff
	v_writelane_b32 v252, s3, 44
	s_cselect_b64 s[2:3], -1, 0
	v_writelane_b32 v252, s2, 45
	s_cmp_eq_u32 s6, 10
	v_mov_b64_e32 v[162:163], 0xaff
	v_writelane_b32 v252, s3, 46
	s_cselect_b64 s[2:3], -1, 0
	v_writelane_b32 v252, s2, 47
	s_cmp_eq_u32 s6, 9
	v_mov_b64_e32 v[164:165], 0xb00
	v_writelane_b32 v252, s3, 48
	s_cselect_b64 s[2:3], -1, 0
	v_writelane_b32 v252, s2, 49
	s_cmp_eq_u32 s6, 8
	v_mov_b32_e32 v233, 0x160
	v_writelane_b32 v252, s3, 50
	s_cselect_b64 s[2:3], -1, 0
	v_writelane_b32 v252, s2, 51
	s_cmp_eq_u32 s6, 7
	v_mov_b32_e32 v234, 0x161
	v_writelane_b32 v252, s3, 52
	s_cselect_b64 s[2:3], -1, 0
	v_writelane_b32 v252, s2, 53
	s_cmp_eq_u32 s6, 6
	v_mov_b32_e32 v235, 0x42800000
	v_writelane_b32 v252, s3, 54
	s_cselect_b64 s[2:3], -1, 0
	v_writelane_b32 v252, s2, 55
	s_cmp_eq_u32 s6, 5
	v_mov_b32_e32 v236, 0x3f80
	v_writelane_b32 v252, s3, 56
	s_cselect_b64 s[2:3], -1, 0
	v_writelane_b32 v252, s2, 57
	s_cmp_eq_u32 s6, 4
	v_mov_b32_e32 v237, 0x3f00
	v_writelane_b32 v252, s3, 58
	s_cselect_b64 s[2:3], -1, 0
	v_writelane_b32 v252, s2, 59
	s_cmp_eq_u32 s6, 3
	s_mov_b32 s92, 0x2aaaaaab
	v_writelane_b32 v252, s3, 60
	s_cselect_b64 s[2:3], -1, 0
	v_writelane_b32 v252, s2, 61
	s_cmp_eq_u32 s6, 2
	s_mov_b32 s37, 0xffff0000
	v_writelane_b32 v252, s3, 62
	s_cselect_b64 s[2:3], -1, 0
	v_writelane_b32 v252, s2, 63
	s_cmp_eq_u32 s6, 1
	s_mov_b32 s79, 0xf800000
	v_writelane_b32 v253, s3, 0
	s_cselect_b64 s[2:3], -1, 0
	v_writelane_b32 v253, s2, 1
	s_cmp_eq_u32 s6, 0
	s_movk_i32 s33, 0x7fff
	v_writelane_b32 v253, s3, 2
	s_cselect_b64 s[2:3], -1, 0
	v_writelane_b32 v253, s2, 3
	s_mov_b32 s72, 0xf149f2ca
	s_mov_b64 s[76:77], 0x2000
	v_writelane_b32 v253, s3, 4
	s_lshl_b32 s2, s6, 8
	s_add_u32 s2, s14, s2
	s_addc_u32 s3, s15, 0
	s_add_u32 s4, s2, 0x1400
	s_addc_u32 s5, s3, 0
	v_writelane_b32 v253, s4, 5
	s_add_u32 s2, s2, 0x2400
	s_addc_u32 s3, s3, 0
	v_writelane_b32 v253, s5, 6
	v_writelane_b32 v253, s2, 7
	s_mov_b32 s95, 0
	s_mov_b32 s36, 0x3e38aa3b
	v_writelane_b32 v253, s3, 8
	s_movk_i32 s2, 0x3ff
	v_and_or_b32 v0, v0, s2, v169
	s_add_u32 s2, s14, 0x3400
	s_addc_u32 s3, s15, 0
	v_writelane_b32 v253, s2, 9
	s_mov_b64 s[22:23], 0x80
	s_nop 0
	v_writelane_b32 v253, s3, 10
	s_add_u32 s2, s14, 0x3500
	s_addc_u32 s3, s15, 0
	v_writelane_b32 v253, s2, 11
	s_nop 1
	v_writelane_b32 v253, s3, 12
	s_waitcnt lgkmcnt(0)
	s_add_u32 s2, s62, 0x3c00
	v_writelane_b32 v253, s2, 13
	v_writelane_b32 v253, s56, 14
	s_addc_u32 s2, s63, 0
	s_nop 0
	v_writelane_b32 v253, s57, 15
	v_writelane_b32 v253, s58, 16
	v_writelane_b32 v253, s59, 17
	v_writelane_b32 v253, s60, 18
	v_writelane_b32 v253, s61, 19
	v_writelane_b32 v253, s62, 20
	v_writelane_b32 v253, s63, 21
	v_writelane_b32 v253, s64, 22
	v_writelane_b32 v253, s65, 23
	v_writelane_b32 v253, s66, 24
	v_writelane_b32 v253, s67, 25
	v_writelane_b32 v253, s68, 26
	v_writelane_b32 v253, s69, 27
	v_writelane_b32 v253, s70, 28
	v_writelane_b32 v253, s71, 29
	v_writelane_b32 v253, s2, 30
	s_add_i32 s2, 0, 0x1d500
	v_writelane_b32 v253, s2, 31
	s_add_i32 s2, 0, 0x1d600
	v_writelane_b32 v253, s2, 32
	s_add_i32 s2, 0, 0xc900
	v_writelane_b32 v253, s2, 33
	s_add_i32 s2, 0, 0x10d00
	v_writelane_b32 v253, s2, 34
	s_add_i32 s2, 0, 0x15100
	v_writelane_b32 v253, s2, 35
	s_add_i32 s2, 0, 0x19100
	v_writelane_b32 v253, s2, 36
	s_add_i32 s2, 0, 0x1d900
	v_writelane_b32 v253, s2, 37
	s_add_i32 s2, 0, 0x1d5fc
	v_writelane_b32 v253, s2, 38
	s_add_i32 s2, 0, 0x1d510
	v_writelane_b32 v253, s2, 39
	s_add_i32 s2, 0, 0x1d520
	v_writelane_b32 v253, s2, 40
	s_add_i32 s2, 0, 0x1d530
	v_writelane_b32 v253, s2, 41
	s_add_i32 s2, 0, 0x1d540
	v_writelane_b32 v253, s2, 42
	s_add_i32 s2, 0, 0x1d550
	v_writelane_b32 v253, s2, 43
	s_add_i32 s2, 0, 0x1d560
	v_writelane_b32 v253, s2, 44
	s_add_i32 s2, 0, 0x1d570
	v_writelane_b32 v253, s2, 45
	s_add_i32 s2, 0, 0x1d580
	v_writelane_b32 v253, s2, 46
	s_add_i32 s2, 0, 0x1d590
	v_writelane_b32 v253, s2, 47
	s_add_i32 s2, 0, 0x1d5a0
	v_writelane_b32 v253, s2, 48
	s_add_i32 s2, 0, 0x1d5b0
	v_writelane_b32 v253, s2, 49
	s_add_i32 s2, 0, 0x1d5c0
	v_writelane_b32 v253, s2, 50
	s_add_i32 s2, 0, 0x1d5d0
	v_writelane_b32 v253, s2, 51
	s_add_i32 s2, 0, 0x1d5e0
	v_writelane_b32 v253, s2, 52
	s_add_i32 s2, 0, 0x1d5f0
	v_writelane_b32 v253, s2, 53
	s_add_i32 s2, 0, 0x23fc0
	v_writelane_b32 v253, s2, 54
	s_add_i32 s2, 0, 0x23fc4
	v_writelane_b32 v253, s2, 55
	v_cmp_eq_u32_e64 s[2:3], 0, v0
	s_movk_i32 s57, 0x300
	s_mov_b32 s62, 0xefa18f08
	v_writelane_b32 v253, s2, 56
	s_nop 1
	v_writelane_b32 v253, s3, 57
	v_writelane_b32 v253, s40, 58
	s_nop 1
	v_writelane_b32 v254, s46, 0
	v_writelane_b32 v254, s47, 1
	v_writelane_b32 v254, s48, 2
	v_writelane_b32 v254, s49, 3
	v_writelane_b32 v254, s50, 4
	v_writelane_b32 v253, s41, 59
	v_writelane_b32 v254, s51, 5
	v_writelane_b32 v253, s42, 60
	v_writelane_b32 v254, s52, 6
	v_writelane_b32 v253, s43, 61
	v_writelane_b32 v254, s53, 7
	v_writelane_b32 v253, s44, 62
	v_writelane_b32 v254, s54, 8
	v_writelane_b32 v253, s45, 63
	v_writelane_b32 v254, s55, 9
	v_readlane_b32 s40, v252, 4
	v_readlane_b32 s41, v252, 5
	v_readlane_b32 s42, v252, 6
	v_readlane_b32 s43, v252, 7
	v_readlane_b32 s44, v252, 8
	v_readlane_b32 s45, v252, 9
	v_readlane_b32 s46, v252, 10
	v_readlane_b32 s47, v252, 11
	v_readlane_b32 s48, v252, 12
	v_readlane_b32 s49, v252, 13
	v_readlane_b32 s50, v252, 14
	v_readlane_b32 s51, v252, 15
	v_readlane_b32 s52, v252, 16
	v_readlane_b32 s53, v252, 17
	v_readlane_b32 s54, v252, 18
	v_readlane_b32 s55, v252, 19
	v_writelane_b32 v254, s89, 10
	s_branch .LBB0_11
	s_nop 0
	s_nop 0
	s_nop 0
	s_nop 0
	s_nop 0
	s_nop 0
	s_nop 0
	s_nop 0
	s_nop 0
	s_nop 0
